# MoBA K/V tiles staged by LDS-DMA into two alternating LDS stages (one barrier per tile) + batched QK/PV fragment reads; GEMM K-loops on LDS-DMA; PEER trims
# speedup vs baseline: 1.0540x; 1.0197x over previous
; __device__ __forceinline__ unsigned xb_add(unsigned* q, unsigned v) { return __hip_atomic_fetch_add(q, v, __ATOMIC_RELAXED, __HIP_MEMORY_SCOPE_AGENT); }
; __global__ void __launch_bounds__(256, 2) fwd_kernel(P p) {
;     ...
;   if (threadIdx.x == 0) {
;     ((volatile unsigned*)(smem + 65520))[0] = 0u;
;     ((volatile unsigned*)(smem + 65520))[1] = 0u;
;     const unsigned x = (unsigned)__builtin_amdgcn_s_getreg((3 << 11) | 20) & 0xFu;
;     (void)xb_add(&((unsigned*)(ws + OFF_BAR))[XB_XCNT(x)], 1u);
_Z10fwd_kernel1P:
	s_load_dwordx2 s[68:69], s[0:1], 0x70
	s_load_dword s78, s[0:1], 0x78
	s_add_u32 s10, s0, 0x78
	s_addc_u32 s11, s1, 0
	s_mov_b64 s[6:7], 0
	s_waitcnt lgkmcnt(0)
	s_add_u32 s8, s68, s6
	s_mov_b32 s26, s2
	s_addc_u32 s9, s69, s7
	v_and_b32_e32 v208, 0x3ff, v0
	v_cmp_eq_u32_e64 s[2:3], 0, v208
	s_mov_b64 s[4:5], exec
	s_nop 0
	v_writelane_b32 v255, s2, 0
	s_nop 1
	v_writelane_b32 v255, s3, 1
	s_and_b64 s[2:3], s[4:5], s[2:3]
	s_mov_b64 exec, s[2:3]
	s_cbranch_execz .LBB0_3
	s_mov_b64 s[2:3], src_shared_base
	v_mov_b32_e32 v2, 0x12000
	v_mov_b32_e32 v3, s3
	v_mov_b32_e32 v1, 0
	s_mov_b64 s[12:13], exec
	flat_store_dword v[2:3], v1 sc0 sc1
	s_waitcnt vmcnt(0)
	v_mov_b32_e32 v2, 0x12004
	flat_store_dword v[2:3], v1 sc0 sc1
	s_waitcnt vmcnt(0)
	v_mbcnt_lo_u32_b32 v1, s12, 0
	v_mbcnt_hi_u32_b32 v1, s13, v1
	v_cmp_eq_u32_e32 vcc, 0, v1
	s_getreg_b32 s2, hwreg(HW_REG_XCC_ID, 0, 4)
	s_and_b64 s[14:15], exec, vcc
	s_mov_b64 exec, s[14:15]
	s_cbranch_execz .LBB0_3
	s_lshl_b32 s2, s2, 8
	s_and_b32 s2, s2, 0xf00
	s_bcnt1_i32_b64 s3, s[12:13]
	v_mov_b32_e32 v1, s2
	v_mov_b32_e32 v2, s3
	global_atomic_add v1, v2, s[8:9] offset:1024

; __device__ __forceinline__ void gbar(unsigned* bar, volatile unsigned* st) {
;   asm volatile("s_waitcnt vmcnt(0) lgkmcnt(0)" ::: "memory");
;   __syncthreads();
;   if (threadIdx.x == 0) {
;     const unsigned x = (unsigned)__builtin_amdgcn_s_getreg((3 << 11) | 20) & 0xFu;
;     unsigned nloc = st[0], nx = st[1];
;     if (nloc == 0u) { xb_complete(bar, x, nloc, nx); st[0] = nloc; st[1] = nx; }
.LBB0_61:
	s_mov_b64 s[6:7], 0
	s_waitcnt vmcnt(0) lgkmcnt(0)
	s_barrier
	s_mov_b64 s[0:1], exec
	v_readlane_b32 s2, v255, 0
	v_readlane_b32 s3, v255, 1
	s_and_b64 s[2:3], s[0:1], s[2:3]
	s_mov_b64 exec, s[2:3]
	s_cbranch_execz .LBB0_113
	s_mov_b64 s[2:3], src_shared_base
	v_mov_b32_e32 v0, 0x12000
	v_mov_b32_e32 v1, s3
	s_getreg_b32 s2, hwreg(HW_REG_XCC_ID, 0, 4)
	flat_load_dword v2, v[0:1] sc0 sc1
	s_waitcnt vmcnt(0)
	v_mov_b32_e32 v0, 0x12004
	flat_load_dword v0, v[0:1] sc0 sc1
	s_waitcnt vmcnt(0)
	s_add_u32 s6, s68, s6
	s_addc_u32 s7, s69, s7
	s_and_b32 s2, s2, 15
	s_waitcnt lgkmcnt(0)
	v_cmp_eq_u32_e32 vcc, 0, v2
	s_and_saveexec_b64 s[8:9], vcc
	s_cbranch_execz .LBB0_77
	s_add_u32 s10, s6, 0x1000
	s_addc_u32 s11, s7, 0
	s_add_u32 s12, s6, 0x1100
	s_addc_u32 s13, s7, 0
	s_add_u32 s14, s6, 0x1200
	s_addc_u32 s15, s7, 0
	s_add_u32 s16, s6, 0x1300
	s_addc_u32 s17, s7, 0
	s_mov_b32 s3, 1
	v_mov_b32_e32 v16, 0
	s_branch .LBB0_65

; __device__ __forceinline__ unsigned xb_ld(unsigned* q) { return __hip_atomic_load(q, __ATOMIC_RELAXED, __HIP_MEMORY_SCOPE_AGENT); }
; __device__ __forceinline__ void xb_complete(unsigned* bar, unsigned x, unsigned& nloc, unsigned& nx) {
;     ...
;     sum = 0u; cnt = 0u; mine = 0u;
; #pragma unroll
;     for (unsigned j = 0; j < 16; ++j) { const unsigned c = xb_ld(&bar[XB_XCNT(j)]); sum += c; cnt += (c > 0u) ? 1u : 0u; mine = (j == x) ? c : mine; }
;     if (sum == G) break;
;     __builtin_amdgcn_s_sleep(1);
;     if ((++sp & 255u) == 0u) { if (xb_ld(&bar[XB_TMO])) break; if (sp > XB_SPIN_CAP) { atomicAdd(&bar[XB_TMO], 1u); break; } }
;   }
;   nloc = mine > 0u ? mine : 1u; nx = cnt > 0u ? cnt : 1u;
; }
; __device__ __forceinline__ void gbar(unsigned* bar, volatile unsigned* st) {
;   asm volatile("s_waitcnt vmcnt(0) lgkmcnt(0)" ::: "memory");
;   __syncthreads();
;   if (threadIdx.x == 0) {
;     const unsigned x = (unsigned)__builtin_amdgcn_s_getreg((3 << 11) | 20) & 0xFu;
;     unsigned nloc = st[0], nx = st[1];
;     if (nloc == 0u) { xb_complete(bar, x, nloc, nx); st[0] = nloc; st[1] = nx; }
.LBB0_76:
	s_cmp_eq_u32 s2, 0
	s_cselect_b64 vcc, -1, 0
	s_cmp_eq_u32 s2, 1
	v_cndmask_b32_e32 v16, 0, v15, vcc
	s_cselect_b64 vcc, -1, 0
	s_cmp_eq_u32 s2, 2
	v_cndmask_b32_e32 v16, v16, v0, vcc
	s_cselect_b64 vcc, -1, 0
	s_cmp_eq_u32 s2, 3
	v_cndmask_b32_e32 v16, v16, v1, vcc
	s_cselect_b64 vcc, -1, 0
	s_cmp_eq_u32 s2, 4
	v_cndmask_b32_e32 v16, v16, v2, vcc
	s_cselect_b64 vcc, -1, 0
	s_cmp_eq_u32 s2, 5
	v_cndmask_b32_e32 v16, v16, v3, vcc
	s_cselect_b64 vcc, -1, 0
	s_cmp_eq_u32 s2, 6
	v_cndmask_b32_e32 v16, v16, v4, vcc
	s_cselect_b64 vcc, -1, 0
	s_cmp_eq_u32 s2, 7
	v_cndmask_b32_e32 v16, v16, v5, vcc
	s_cselect_b64 vcc, -1, 0
	s_cmp_eq_u32 s2, 8
	v_cndmask_b32_e32 v16, v16, v6, vcc
	s_cselect_b64 vcc, -1, 0
	s_cmp_eq_u32 s2, 9
	v_cndmask_b32_e32 v16, v16, v7, vcc
	s_cselect_b64 vcc, -1, 0
	s_cmp_eq_u32 s2, 10
	v_cndmask_b32_e32 v16, v16, v8, vcc
	s_cselect_b64 vcc, -1, 0
	s_cmp_eq_u32 s2, 11
	v_cndmask_b32_e32 v16, v16, v9, vcc
	s_cselect_b64 vcc, -1, 0
	s_cmp_eq_u32 s2, 12
	v_cndmask_b32_e32 v16, v16, v10, vcc
	s_cselect_b64 vcc, -1, 0
	s_cmp_eq_u32 s2, 13
	v_cndmask_b32_e32 v16, v16, v11, vcc
	s_cselect_b64 vcc, -1, 0
	s_cmp_eq_u32 s2, 14
	v_cndmask_b32_e32 v16, v16, v12, vcc
	s_cselect_b64 vcc, -1, 0
	s_cmp_eq_u32 s2, 15
	v_cndmask_b32_e32 v16, v16, v13, vcc
	s_cselect_b64 vcc, -1, 0
	v_cndmask_b32_e32 v16, v16, v14, vcc
	v_cmp_ne_u32_e32 vcc, 0, v15
	s_mov_b64 s[4:5], src_shared_base
	s_nop 0
	v_cndmask_b32_e64 v15, 0, 1, vcc
	v_cmp_ne_u32_e32 vcc, 0, v0
	s_nop 1
	v_addc_co_u32_e32 v0, vcc, 0, v15, vcc
	v_cmp_ne_u32_e32 vcc, 0, v1
	s_nop 1
	v_cndmask_b32_e64 v1, 0, 1, vcc
	v_cmp_ne_u32_e32 vcc, 0, v2
	v_max_u32_e32 v2, 1, v16
	s_nop 0
	v_addc_co_u32_e32 v0, vcc, v0, v1, vcc
	v_cmp_ne_u32_e32 vcc, 0, v3
	s_nop 1
	v_cndmask_b32_e64 v1, 0, 1, vcc
	v_cmp_ne_u32_e32 vcc, 0, v4
	v_mov_b32_e32 v4, 0x12000
	s_nop 0
	v_addc_co_u32_e32 v0, vcc, v0, v1, vcc
	v_cmp_ne_u32_e32 vcc, 0, v5
	v_mov_b32_e32 v5, s5
	flat_store_dword v[4:5], v2 sc0 sc1
	s_waitcnt vmcnt(0)
	v_cndmask_b32_e64 v1, 0, 1, vcc
	v_cmp_ne_u32_e32 vcc, 0, v6
	v_mov_b32_e32 v4, 0x12004
	s_nop 0
	v_addc_co_u32_e32 v0, vcc, v0, v1, vcc
	v_cmp_ne_u32_e32 vcc, 0, v7
	s_nop 1
	v_cndmask_b32_e64 v1, 0, 1, vcc
	v_cmp_ne_u32_e32 vcc, 0, v8
	s_nop 1
	v_addc_co_u32_e32 v0, vcc, v0, v1, vcc
	v_cmp_ne_u32_e32 vcc, 0, v9
	s_nop 1
	v_cndmask_b32_e64 v1, 0, 1, vcc
	v_cmp_ne_u32_e32 vcc, 0, v10
	s_nop 1
	v_addc_co_u32_e32 v0, vcc, v0, v1, vcc
	v_cmp_ne_u32_e32 vcc, 0, v11
	s_nop 1
	v_cndmask_b32_e64 v1, 0, 1, vcc
	v_cmp_ne_u32_e32 vcc, 0, v12
	s_nop 1
	v_addc_co_u32_e32 v0, vcc, v0, v1, vcc
	v_cmp_ne_u32_e32 vcc, 0, v13
	s_nop 1
	v_cndmask_b32_e64 v1, 0, 1, vcc
	v_cmp_ne_u32_e32 vcc, 0, v14
	s_nop 1
	v_addc_co_u32_e32 v0, vcc, v0, v1, vcc
	v_max_u32_e32 v0, 1, v0
	flat_store_dword v[4:5], v0 sc0 sc1
	s_waitcnt vmcnt(0)

; __device__ __forceinline__ int otid() { int t = threadIdx.x; asm volatile("" : "+v"(t)); return t; }
; __device__ __forceinline__ char* opaque(char* q) { size_t z = 0; asm volatile("" : "+s"(z)); return q + z; }
; __global__ void __launch_bounds__(256, 2) fwd_kernel(P p) {
;     ...
;   gbar((unsigned*)(opaque(p.ws) + OFF_BAR), (volatile unsigned*)(smem + 65520));
;   if (STOP == 1) return;
;   for (int layer = 0; layer < 4; ++layer) {
;     const int li2 = layer >> 1;
;     ws = opaque(p.ws);
;     const int tid = otid();
;     const bf16_t* XN = (const bf16_t*)(ws + OFF_XN);
;     float* H = (float*)(ws + OFF_H);
;     if ((layer & 1) == 0) {
.LBB0_113:
	v_writelane_b32 v255, s52, 22
	s_nop 1
	v_writelane_b32 v255, s53, 23
	v_writelane_b32 v255, s54, 24
	v_writelane_b32 v255, s55, 25
	v_writelane_b32 v255, s56, 26
	v_writelane_b32 v255, s57, 27
	v_writelane_b32 v255, s58, 28
	v_writelane_b32 v255, s59, 29
	v_writelane_b32 v255, s60, 30
	v_writelane_b32 v255, s61, 31
	v_writelane_b32 v255, s62, 32
	v_writelane_b32 v255, s63, 33
	v_writelane_b32 v255, s64, 34
	v_writelane_b32 v255, s65, 35
	v_writelane_b32 v255, s66, 36
	v_writelane_b32 v255, s67, 37
	s_or_b64 exec, exec, s[0:1]
	s_lshl_b32 s70, s78, 8
	s_cmpk_gt_i32 s26, 0x1ff
	s_cselect_b64 s[0:1], -1, 0
	v_writelane_b32 v255, s0, 38
	v_mov_b32_e32 v1, 0
	v_mov_b32_e32 v4, v1
	v_writelane_b32 v255, s1, 39
	s_and_b32 s0, s26, 0x100
	s_cmp_eq_u32 s0, 0
	s_cselect_b64 s[2:3], -1, 0
	v_writelane_b32 v255, s2, 40
	s_cmp_lg_u32 s0, 0
	s_cselect_b64 s[0:1], -1, 0
	v_writelane_b32 v255, s3, 41
	v_writelane_b32 v255, s0, 42
	s_cmpk_lt_i32 s26, 0x400
	v_mov_b32_e32 v5, v1
	v_writelane_b32 v255, s1, 43
	s_cselect_b64 s[0:1], -1, 0
	v_writelane_b32 v255, s0, 44
	s_cmpk_lt_i32 s26, 0x1000
	v_mov_b32_e32 v6, v1
	v_writelane_b32 v255, s1, 45
	s_cselect_b64 s[0:1], -1, 0
	v_writelane_b32 v255, s0, 46
	s_lshl_b32 s71, s78, 3
	s_lshl_b32 s76, s78, 4
	v_writelane_b32 v255, s1, 47
	s_lshl_b32 s0, s26, 3
	v_writelane_b32 v255, s0, 48
	s_lshl_b32 s0, s26, 11
	v_writelane_b32 v255, s0, 49
	s_lshl_b32 s0, s78, 11
	v_writelane_b32 v255, s0, 50
	s_lshl_b32 s0, s26, 4
	v_writelane_b32 v255, s0, 51
	s_lshl_b32 s0, s26, 7
	v_writelane_b32 v255, s0, 52
	s_mov_b32 s0, s26
	v_writelane_b32 v255, s0, 53
	s_lshl_b32 s77, s78, 7
	s_lshl_b32 s92, s78, 10
	v_writelane_b32 v255, s1, 54
	s_lshl_b32 s0, s26, 10
	v_writelane_b32 v255, s0, 55
	s_add_u32 s0, s68, 0x1da84080
	v_writelane_b32 v255, s0, 56
	s_addc_u32 s0, s69, 0
	v_writelane_b32 v255, s0, 57
	v_mov_b32_e32 v7, v1
	v_mov_b32_e32 v8, v1
	v_mov_b32_e32 v9, v1
	v_mov_b32_e32 v10, v1
	v_mov_b32_e32 v11, v1
	v_mov_b32_e32 v12, v1
	v_mov_b32_e32 v13, v1
	v_mov_b32_e32 v14, v1
	v_mov_b32_e32 v15, v1
	v_mov_b32_e32 v0, v1
	v_mov_b32_e32 v2, v1
	v_mov_b32_e32 v3, v1
	v_mov_b64_e32 v[18:19], v[14:15]
	v_writelane_b32 v255, s68, 58
	s_movk_i32 s33, 0x70
	s_mov_b32 s93, 0x10000
	s_mov_b32 s46, 0x20000
	s_mov_b32 s47, 0x30000
	s_mov_b32 s50, 0x40000
	s_mov_b32 s51, 0x50000
	s_mov_b32 s94, 0x17a84000
	s_mov_b32 s5, 0x17a94000
	s_mov_b32 s2, 0x17aa4000
	s_mov_b32 s3, 0x17ab4000
	s_mov_b32 s64, 0x17ac4000
	s_mov_b32 s96, 0x17ad4000
	s_mov_b32 s97, 0x17ae4000
	s_mov_b32 s87, 0x17af4000
	s_movk_i32 s89, 0xff
	v_mov_b32_e32 v209, 0x1000
	v_mov_b32_e32 v211, 0x2000
	s_mov_b32 s90, 0xffff0000
	s_mov_b32 s72, 0x25a84000
	s_mov_b32 s73, 0x25a94000
	s_mov_b32 s74, 0x25aa4000
	s_mov_b32 s75, 0x25ab4000
	s_mov_b32 s91, 0x25ac4000
	s_mov_b32 s80, 0x25ad4000
	s_mov_b32 s81, 0x25ae4000
	s_mov_b32 s95, 0x25af4000
	s_mov_b32 s60, 0x2a4000
	s_mov_b32 s4, 0x2b4000
	s_movk_i32 s83, 0xff80
	s_movk_i32 s61, 0x7f
	s_mov_b32 s53, 0xc2fc0000
	s_mov_b32 s88, 0x5040100
	v_mov_b32_e32 v210, 0x358637bd
	v_mov_b32_e32 v238, 0x7f7f7f7f
	v_mov_b32_e32 v239, 0x77777777
	v_mov_b32_e32 v240, 0x3ba10414
	v_mov_b32_e32 v212, 0x12000
	v_mov_b32_e32 v214, 0x12004
	v_not_b32_e32 v241, 63
	v_mov_b32_e32 v242, 0x42800000
	v_mbcnt_hi_u32_b32 v243, -1, v110
	v_mov_b32_e32 v244, 0xff800000
	v_mov_b32_e32 v250, v1
	v_mov_b32_e32 v251, v1
	v_bfrev_b32_e32 v245, 1
	v_mov_b32_e32 v246, 0xb9c68948
	v_mov_b32_e32 v247, 0x7f800000
	v_mov_b64_e32 v[16:17], v[12:13]
	v_mov_b64_e32 v[14:15], v[10:11]
	v_mov_b64_e32 v[12:13], v[8:9]
	v_mov_b64_e32 v[10:11], v[6:7]
	v_mov_b64_e32 v[8:9], v[4:5]
	v_mov_b64_e32 v[6:7], v[2:3]
	v_mov_b64_e32 v[4:5], v[0:1]
	s_mov_b32 s82, 0x27a84000
	s_movk_i32 s52, 0xff00
	s_mov_b32 s67, 0
	s_mov_b64 s[6:7], 0
	s_mov_b64 s[84:85], 0x2000
	v_writelane_b32 v255, s69, 59
	s_waitcnt lgkmcnt(0)
	s_barrier
	s_branch .LBB0_116

; __device__ void moba_item(const P& p, int bh, int qt, char* smem) {
;     ...
;   const unsigned mymask = sMask[w * 16 + li];
;   const int qpos = q0 + w * 16 + li;
;   bf16x8 qf[4];
; #pragma unroll
;   for (int kk = 0; kk < 4; ++kk) qf[kk] = *(const bf16x8*)(Q + (size_t)qpos * 128 + (kk * 4 + g) * 8);
;   f32x4 oacc[8];
; #pragma unroll
;   for (int d = 0; d < 8; ++d) oacc[d] = (f32x4){0.f, 0.f, 0.f, 0.f};
;   float mrun = -INFINITY, lrun = 0.f;
;   const int ntiles = qblk * 4 + qin + 1;
;   const int kr = tid >> 4, kc = tid & 15;
;   const int vr = tid >> 3, vc = tid & 7;
;   u32x4 rkA[4], rvA[4], rkB[4], rvB[4];
; #pragma unroll
;   for (int i = 0; i < 4; ++i) {
;     rkA[i] = *(const u32x4*)(Kp + (size_t)(kr + 16 * i) * 128 + kc * 8);
;     rvA[i] = *(const u32x4*)(VT + (size_t)(vr + 32 * i) * 4096 + vc * 8);
;   }
;   if (ntiles > 1) {
; #pragma unroll
;     for (int i = 0; i < 4; ++i) {
;       rkB[i] = *(const u32x4*)(Kp + (size_t)(64 + kr + 16 * i) * 128 + kc * 8);
;       rvB[i] = *(const u32x4*)(VT + (size_t)(vr + 32 * i) * 4096 + 64 + vc * 8);
;     }
;   }
.LBB0_608:
	s_or_b64 exec, exec, s[10:11]
	v_and_b32_e32 v0, -16, v93
	v_and_b32_e32 v76, 15, v2
	v_add_u32_e32 v0, s42, v0
	v_or_b32_e32 v148, v0, v76
	s_lshl_b32 s0, s44, 19
	v_ashrrev_i32_e32 v149, 31, v148
	s_lshl_b32 s0, s0, 1
	v_bfe_u32 v3, v2, 4, 2
	v_lshlrev_b64 v[20:21], 8, v[148:149]
	s_add_u32 s0, s22, s0
	v_lshl_add_u64 v[20:21], s[24:25], 0, v[20:21]
	v_lshlrev_b32_e32 v0, 4, v3
	s_addc_u32 s1, s23, 0
	v_lshl_add_u64 v[32:33], v[20:21], 0, v[0:1]
	v_ashrrev_i32_e32 v150, 4, v2
	v_ashrrev_i32_e32 v52, 3, v2
	v_lshlrev_b32_e32 v0, 4, v76
	s_add_u32 s6, s22, s43
	v_lshl_add_u64 v[36:37], s[0:1], 0, v[0:1]
	s_mov_b64 s[0:1], 0x1aa84000
	v_ashrrev_i32_e32 v151, 31, v150
	v_ashrrev_i32_e32 v53, 31, v52
	s_addc_u32 s7, s23, 0
	v_lshl_add_u64 v[152:153], v[36:37], 0, s[0:1]
	v_lshlrev_b64 v[36:37], 8, v[150:151]
	v_lshlrev_b64 v[68:69], 13, v[52:53]
	s_mov_b64 s[0:1], 0x40000
	s_add_u32 s6, s6, 0x1ba84000
	v_and_b32_e32 v77, 7, v2
	v_lshl_add_u64 v[74:75], v[152:153], 0, v[36:37]
	v_add_u32_e32 v54, 16, v150
	v_lshl_add_u64 v[70:71], v[68:69], 0, s[0:1]
	s_movk_i32 s0, 0x2000
	s_addc_u32 s7, s7, 0
	v_lshlrev_b32_e32 v0, 4, v77
	v_ashrrev_i32_e32 v55, 31, v54
	v_add_co_u32_e32 v56, vcc, s0, v74
	s_mov_b64 s[0:1], 0x80000
	v_lshl_add_u64 v[62:63], s[6:7], 0, v[0:1]
	v_lshlrev_b64 v[44:45], 8, v[54:55]
	v_lshl_add_u64 v[72:73], v[68:69], 0, s[0:1]
	v_lshl_add_u64 v[40:41], v[62:63], 0, v[68:69]
	v_lshl_add_u64 v[44:45], v[152:153], 0, v[44:45]
	v_lshl_add_u64 v[48:49], v[62:63], 0, v[70:71]
	v_addc_co_u32_e32 v57, vcc, 0, v75, vcc
	v_lshl_add_u64 v[60:61], v[62:63], 0, v[72:73]
	s_waitcnt lgkmcnt(0)
	s_barrier
	global_load_dwordx4 v[20:23], v[32:33], off
	global_load_dwordx4 v[24:27], v[32:33], off offset:64
	global_load_dwordx4 v[28:31], v[32:33], off offset:128
	s_nop 0
	global_load_dwordx4 v[32:35], v[32:33], off offset:192
	s_nop 0
	s_nop 0
	s_nop 0
	s_nop 0
	s_nop 0
	s_nop 0
	v_add_u32_e32 v60, 48, v150
	v_ashrrev_i32_e32 v61, 31, v60
	v_lshlrev_b64 v[78:79], 8, v[60:61]
	s_mov_b64 s[0:1], 0xc0000
	v_lshl_add_u64 v[78:79], v[152:153], 0, v[78:79]
	v_lshl_add_u64 v[80:81], v[68:69], 0, s[0:1]
	v_lshl_add_u64 v[62:63], v[62:63], 0, v[80:81]
	v_bfi_b32 v0, -16, v93, v2
	v_lshlrev_b32_e32 v0, 2, v0
	ds_read_b32 v149, v0 offset:36864
	v_lshlrev_b32_e32 v0, 3, v77
	s_cmp_lt_i32 s40, 1
	v_lshl_add_u64 v[62:63], s[6:7], 0, v[68:69]
	v_lshl_add_u64 v[68:69], s[6:7], 0, v[70:71]
	v_lshl_add_u64 v[70:71], s[6:7], 0, v[72:73]
	v_lshl_add_u64 v[72:73], s[6:7], 0, v[80:81]
	v_lshlrev_b32_e32 v0, 1, v0
	s_cbranch_scc1 .LBB0_610
	v_add_co_u32_e32 v78, vcc, 0x4000, v74
	v_lshl_add_u64 v[92:93], v[62:63], 0, v[0:1]
	s_nop 0
	v_addc_co_u32_e32 v79, vcc, 0, v75, vcc
	s_nop 0
	v_add_co_u32_e32 v78, vcc, 0x5000, v74
	v_lshl_add_u64 v[100:101], v[68:69], 0, v[0:1]
	s_nop 0
	v_addc_co_u32_e32 v79, vcc, 0, v75, vcc
	s_nop 0
	v_add_co_u32_e32 v78, vcc, 0x6000, v74
	v_lshl_add_u64 v[104:105], v[70:71], 0, v[0:1]
	s_nop 0
	v_addc_co_u32_e32 v79, vcc, 0, v75, vcc
	v_add_co_u32_e32 v74, vcc, 0x7000, v74
	v_addc_co_u32_e32 v75, vcc, 0, v75, vcc
	v_lshl_add_u64 v[78:79], v[72:73], 0, v[0:1]
; __device__ void moba_item(const P& p, int bh, int qt, char* smem) {
;     ...
;   f32x4 oacc[8];
; #pragma unroll
;   for (int d = 0; d < 8; ++d) oacc[d] = (f32x4){0.f, 0.f, 0.f, 0.f};
;   float mrun = -INFINITY, lrun = 0.f;
;   const int ntiles = qblk * 4 + qin + 1;
;   const int kr = tid >> 4, kc = tid & 15;
;   const int vr = tid >> 3, vc = tid & 7;
;   u32x4 rkA[4], rvA[4], rkB[4], rvB[4];
; #pragma unroll
;   for (int i = 0; i < 4; ++i) {
;     rkA[i] = *(const u32x4*)(Kp + (size_t)(kr + 16 * i) * 128 + kc * 8);
;     rvA[i] = *(const u32x4*)(VT + (size_t)(vr + 32 * i) * 4096 + vc * 8);
;   }
;   if (ntiles > 1) {
; #pragma unroll
;     for (int i = 0; i < 4; ++i) {
;       rkB[i] = *(const u32x4*)(Kp + (size_t)(64 + kr + 16 * i) * 128 + kc * 8);
;       rvB[i] = *(const u32x4*)(VT + (size_t)(vr + 32 * i) * 4096 + 64 + vc * 8);
;     }
;   }
;   const float SC = 0.12751743082459868f;
;   auto step = [&](const int tt, u32x4 (&rk)[4], u32x4 (&rv)[4]) __attribute__((always_inline)) {
;     __syncthreads();
; #pragma unroll
;     for (int i = 0; i < 4; ++i) {
;       const int row = kr + 16 * i;
;       const int f = ((row >> 3) & 3) * 4 + (row & 3);
;       *(u32x4*)(sK + row * 256 + ((kc ^ f) << 4)) = rk[i];
;       const int vrow = vr + 32 * i;
;       *(u32x4*)(sV + vrow * 128 + ((vc ^ (vrow & 7)) << 4)) = rv[i];
;     }
.LBB0_610:
	s_cmp_lt_i32 s40, 0
	v_lshlrev_b32_e32 v154, 3, v3
	s_cbranch_scc1 .LBB0_453
	v_lshlrev_b32_e32 v61, 7, v52
	v_xor_b32_e32 v52, v52, v2
	v_lshl_add_u64 v[156:157], v[62:63], 0, v[0:1]
	v_lshl_add_u64 v[158:159], v[68:69], 0, v[0:1]
	v_lshl_add_u64 v[160:161], v[70:71], 0, v[0:1]
	v_lshl_add_u64 v[162:163], v[72:73], 0, v[0:1]
	v_lshlrev_b32_e32 v0, 1, v76
	v_and_b32_e32 v2, 3, v2
	v_and_or_b32 v0, v0, 24, v2
	v_lshlrev_b32_e32 v155, 8, v0
	v_bitop3_b32 v0, v3, v76, 4 bitop3:0x36
	v_lshrrev_b32_e32 v53, 1, v150
	v_lshrrev_b32_e32 v74, 1, v54
	v_lshrrev_b32_e32 v75, 1, v60
	v_lshlrev_b32_e32 v178, 4, v0
	v_bitop3_b32 v0, v3, v76, 8 bitop3:0x36
	v_and_b32_e32 v53, 12, v53
	v_and_b32_e32 v74, 12, v74
	v_and_b32_e32 v75, 12, v75
	v_lshlrev_b32_e32 v179, 4, v0
	v_bitop3_b32 v0, v3, v76, 12 bitop3:0x36
	v_bitop3_b32 v53, v53, v76, v3 bitop3:0x36
	v_lshlrev_b32_e32 v52, 4, v52
	v_bitop3_b32 v74, v74, v76, v3 bitop3:0x36
	v_bitop3_b32 v75, v75, v76, v3 bitop3:0x36
	v_xor_b32_e32 v2, v3, v76
	v_lshlrev_b32_e32 v180, 4, v0
	v_xor_b32_e32 v0, v3, v77
	v_lshlrev_b32_e32 v55, 8, v150
	v_lshlrev_b32_e32 v53, 4, v53
	v_and_b32_e32 v52, 0x70, v52
	v_lshlrev_b32_e32 v54, 8, v54
	v_lshlrev_b32_e32 v74, 4, v74
	v_lshlrev_b32_e32 v60, 8, v60
	v_lshlrev_b32_e32 v75, 4, v75
	v_lshlrev_b32_e32 v151, 4, v2
	v_lshlrev_b32_e32 v182, 4, v0
	v_bitop3_b32 v0, v3, v77, 4 bitop3:0x36
	v_mov_b32_e32 v2, v1
	v_mov_b32_e32 v3, v1
	v_lshlrev_b32_e32 v181, 7, v76
	v_lshlrev_b32_e32 v183, 4, v0
	v_mov_b32_e32 v0, v1
	v_add_u32_e32 v184, v55, v53
	v_add_u32_e32 v185, v61, v52
	v_add_u32_e32 v186, v54, v74
	v_add_u32_e32 v187, v60, v75
	v_mov_b64_e32 v[106:107], v[2:3]
	v_mov_b64_e32 v[54:55], v[2:3]
	v_mov_b64_e32 v[74:75], v[2:3]
	v_mov_b64_e32 v[62:63], v[2:3]
	v_mov_b64_e32 v[78:79], v[2:3]
	v_mov_b64_e32 v[70:71], v[2:3]
	v_mov_b64_e32 v[114:115], v[2:3]
	v_mov_b64_e32 v[110:111], v[2:3]
	s_add_i32 s24, s40, -1
	s_mov_b32 s25, 0
	v_mov_b32_e32 v189, 0xff800000
	v_mov_b32_e32 v188, 0
	v_mov_b64_e32 v[104:105], v[0:1]
	v_mov_b64_e32 v[52:53], v[0:1]
	v_mov_b64_e32 v[72:73], v[0:1]
	v_mov_b64_e32 v[60:61], v[0:1]
	v_mov_b64_e32 v[76:77], v[0:1]
	v_mov_b64_e32 v[68:69], v[0:1]
	v_mov_b64_e32 v[112:113], v[0:1]
	v_mov_b64_e32 v[108:109], v[0:1]
	v_lshrrev_b32_e32 v236, 6, v208
	s_nop 0
	v_readfirstlane_b32 s79, v236
	s_lshl_b32 s79, s79, 10
	v_bfe_u32 v237, v208, 4, 2
	v_bfe_u32 v252, v208, 7, 1
	v_lshl_or_b32 v252, v252, 2, v237
	v_and_b32_e32 v253, 15, v208
	v_xor_b32_e32 v252, v252, v253
	v_lshlrev_b32_e32 v252, 4, v252
	v_lshrrev_b32_e32 v253, 4, v208
	v_lshl_or_b32 v252, v253, 8, v252
	v_xor_b32_e32 v253, 0x80, v252
	v_bfe_u32 v254, v208, 3, 3
	v_and_b32_e32 v237, 7, v208
	v_xor_b32_e32 v237, v237, v254
	v_lshlrev_b32_e32 v237, 4, v237
	v_lshl_or_b32 v254, v254, 13, v237
	s_mov_b32 s32, s25
	v_readfirstlane_b32 s98, v152
	v_readfirstlane_b32 s99, v153
	s_lshl_b32 s57, s32, 8
	s_add_u32 s98, s98, s57
	s_addc_u32 s99, s99, 0
	s_add_u32 m0, s79, 0x0
	s_nop 0
	global_load_lds_dwordx4 v252, s[98:99]
	s_add_u32 m0, s79, 0x1000
	s_add_u32 s98, s98, 0x1000
	s_addc_u32 s99, s99, 0
	global_load_lds_dwordx4 v253, s[98:99]
	s_add_u32 m0, s79, 0x2000
	s_add_u32 s98, s98, 0x1000
	s_addc_u32 s99, s99, 0
	global_load_lds_dwordx4 v252, s[98:99]
	s_add_u32 m0, s79, 0x3000
	s_add_u32 s98, s98, 0x1000
	s_addc_u32 s99, s99, 0
	global_load_lds_dwordx4 v253, s[98:99]
	v_readfirstlane_b32 s98, v156
	v_readfirstlane_b32 s99, v157
	s_lshl_b32 s57, s32, 1
	s_add_u32 s98, s98, s57
	s_addc_u32 s99, s99, 0
	s_add_u32 m0, s79, 0x4000
	s_nop 0
	global_load_lds_dwordx4 v254, s[98:99]
	s_add_u32 m0, s79, 0x5000
	s_add_u32 s98, s98, 0x40000
	s_addc_u32 s99, s99, 0
	global_load_lds_dwordx4 v254, s[98:99]
	s_add_u32 m0, s79, 0x6000
	s_add_u32 s98, s98, 0x40000
	s_addc_u32 s99, s99, 0
	global_load_lds_dwordx4 v254, s[98:99]
	s_add_u32 m0, s79, 0x7000
	s_add_u32 s98, s98, 0x40000
	s_addc_u32 s99, s99, 0
	global_load_lds_dwordx4 v254, s[98:99]
	s_mov_b32 s27, 0
	s_branch .LBB0_614

; __device__ void moba_item(const P& p, int bh, int qt, char* smem) {
;     ...
;   auto step = [&](const int tt, u32x4 (&rk)[4], u32x4 (&rv)[4]) __attribute__((always_inline)) {
;     __syncthreads();
; #pragma unroll
;     for (int i = 0; i < 4; ++i) {
;       const int row = kr + 16 * i;
;       const int f = ((row >> 3) & 3) * 4 + (row & 3);
;       *(u32x4*)(sK + row * 256 + ((kc ^ f) << 4)) = rk[i];
;       const int vrow = vr + 32 * i;
;       *(u32x4*)(sV + vrow * 128 + ((vc ^ (vrow & 7)) << 4)) = rv[i];
;     }
;     __syncthreads();
;     if (tt + 2 < ntiles) {
;       const int k1 = (tt + 2) * 64;
; #pragma unroll
;       for (int i = 0; i < 4; ++i) {
;         rk[i] = *(const u32x4*)(Kp + (size_t)(k1 + kr + 16 * i) * 128 + kc * 8);
;         rv[i] = *(const u32x4*)(VT + (size_t)(vr + 32 * i) * 4096 + k1 + vc * 8);
;       }
;     }
;     const int blk = tt >> 2;
;     const bool own = (blk == qblk);
;     const bool rowvalid = own || ((mymask >> blk) & 1u);
;     if (__any(rowvalid)) {
;       const int key0 = tt * 64;
;       f32x4 sacc[2][2];
; #pragma unroll
;       for (int st = 0; st < 2; ++st)
; #pragma unroll
;         for (int kt = 0; kt < 2; ++kt) {
;           sacc[st][kt] = (f32x4){0.f, 0.f, 0.f, 0.f};
;           const int row = 32 * st + 8 * (li >> 2) + 4 * kt + (li & 3);
; #pragma unroll
;           for (int kk = 0; kk < 4; ++kk) {
;             const bf16x8 kf = *(const bf16x8*)(sK + row * 256 + (((kk * 4 + g) ^ li) << 4));
;             sacc[st][kt] = __builtin_amdgcn_mfma_f32_16x16x32_bf16(kf, qf[kk], sacc[st][kt], 0, 0, 0);
;           }
;         }
.LBB0_614:
	s_add_i32 s26, s27, 2
	s_cmp_gt_i32 s26, s40
	s_cselect_b64 s[8:9], -1, 0
	s_waitcnt vmcnt(0) lgkmcnt(0)
	s_barrier
	s_cmp_ge_i32 s27, s40
	s_cbranch_scc1 .Lmoba_skipA
	s_add_i32 s32, s25, 64
	v_readfirstlane_b32 s98, v152
	v_readfirstlane_b32 s99, v153
	s_lshl_b32 s57, s32, 8
	s_add_u32 s98, s98, s57
	s_addc_u32 s99, s99, 0
	s_add_u32 m0, s79, 0x8000
	s_nop 0
	global_load_lds_dwordx4 v252, s[98:99]
	s_add_u32 m0, s79, 0x9000
	s_add_u32 s98, s98, 0x1000
	s_addc_u32 s99, s99, 0
	global_load_lds_dwordx4 v253, s[98:99]
	s_add_u32 m0, s79, 0xa000
	s_add_u32 s98, s98, 0x1000
	s_addc_u32 s99, s99, 0
	global_load_lds_dwordx4 v252, s[98:99]
	s_add_u32 m0, s79, 0xb000
	s_add_u32 s98, s98, 0x1000
	s_addc_u32 s99, s99, 0
	global_load_lds_dwordx4 v253, s[98:99]
	v_readfirstlane_b32 s98, v156
	v_readfirstlane_b32 s99, v157
	s_lshl_b32 s57, s32, 1
	s_add_u32 s98, s98, s57
	s_addc_u32 s99, s99, 0
	s_add_u32 m0, s79, 0xc000
	s_nop 0
	global_load_lds_dwordx4 v254, s[98:99]
	s_add_u32 m0, s79, 0xd000
	s_add_u32 s98, s98, 0x40000
	s_addc_u32 s99, s99, 0
	global_load_lds_dwordx4 v254, s[98:99]
	s_add_u32 m0, s79, 0xe000
	s_add_u32 s98, s98, 0x40000
	s_addc_u32 s99, s99, 0
	global_load_lds_dwordx4 v254, s[98:99]
	s_add_u32 m0, s79, 0xf000
	s_add_u32 s98, s98, 0x40000
	s_addc_u32 s99, s99, 0
	global_load_lds_dwordx4 v254, s[98:99]
.Lmoba_skipA:
.LBB0_616:
	s_lshr_b32 s6, s27, 2
	s_cmp_eq_u32 s6, s41
	s_cselect_b64 s[0:1], -1, 0
	s_lshl_b32 s6, 1, s6
	v_and_b32_e32 v0, s6, v149
	v_cmp_ne_u32_e32 vcc, 0, v0
	s_or_b64 s[6:7], s[0:1], vcc
	s_mov_b64 vcc, s[6:7]
	s_cbranch_vccz .LBB0_625
	v_add_u32_e32 v0, v155, v151
	v_add_u32_e32 v2, v155, v178
	v_add_u32_e32 v3, v155, v179
	v_add_u32_e32 v168, v155, v180
	s_cmp_eq_u32 s40, s27
	s_cselect_b64 s[0:1], -1, 0
	s_and_b64 vcc, exec, s[0:1]
	s_mov_b64 s[10:11], s[0:1]
	ds_read_b128 v[194:197], v0
	ds_read_b128 v[198:201], v0 offset:1024
	ds_read_b128 v[202:205], v0 offset:8192
	ds_read_b128 v[220:223], v0 offset:9216
	ds_read_b128 v[224:227], v2
	ds_read_b128 v[228:231], v2 offset:1024
	ds_read_b128 v[232:235], v2 offset:8192
	ds_read_b128 v[4:7], v2 offset:9216
	ds_read_b128 v[8:11], v3
	ds_read_b128 v[12:15], v3 offset:1024
	ds_read_b128 v[16:19], v3 offset:8192
	ds_read_b128 v[164:167], v3 offset:9216
	s_waitcnt lgkmcnt(8)
	v_mfma_f32_16x16x32_bf16 v[132:135], v[194:197], v[20:23], 0
	v_mfma_f32_16x16x32_bf16 v[140:143], v[198:201], v[20:23], 0
	v_mfma_f32_16x16x32_bf16 v[136:139], v[202:205], v[20:23], 0
	v_mfma_f32_16x16x32_bf16 v[144:147], v[220:223], v[20:23], 0
	ds_read_b128 v[194:197], v168
	ds_read_b128 v[198:201], v168 offset:1024
	ds_read_b128 v[202:205], v168 offset:8192
	ds_read_b128 v[220:223], v168 offset:9216
	s_waitcnt lgkmcnt(8)
	v_mfma_f32_16x16x32_bf16 v[132:135], v[224:227], v[24:27], v[132:135]
	v_mfma_f32_16x16x32_bf16 v[140:143], v[228:231], v[24:27], v[140:143]
	v_mfma_f32_16x16x32_bf16 v[136:139], v[232:235], v[24:27], v[136:139]
	v_mfma_f32_16x16x32_bf16 v[144:147], v[4:7], v[24:27], v[144:147]
	s_waitcnt lgkmcnt(4)
	v_mfma_f32_16x16x32_bf16 v[132:135], v[8:11], v[28:31], v[132:135]
	v_mfma_f32_16x16x32_bf16 v[140:143], v[12:15], v[28:31], v[140:143]
	v_mfma_f32_16x16x32_bf16 v[136:139], v[16:19], v[28:31], v[136:139]
	v_mfma_f32_16x16x32_bf16 v[144:147], v[164:167], v[28:31], v[144:147]
	s_waitcnt lgkmcnt(0)
	v_mfma_f32_16x16x32_bf16 v[132:135], v[194:197], v[32:35], v[132:135]
	v_mfma_f32_16x16x32_bf16 v[140:143], v[198:201], v[32:35], v[140:143]
	v_mfma_f32_16x16x32_bf16 v[136:139], v[202:205], v[32:35], v[136:139]
	v_mfma_f32_16x16x32_bf16 v[144:147], v[220:223], v[32:35], v[144:147]
	s_nop 7
	s_cbranch_vccnz .LBB0_620
	v_cndmask_b32_e64 v0, 0, 1, s[6:7]
	v_cmp_ne_u32_e32 vcc, 0, v0
	s_cmp_eq_u64 vcc, exec
	s_mov_b64 s[10:11], -1
	s_cbranch_scc0 .LBB0_620
	s_mov_b32 s28, 0x3e0293ee
	v_pk_mul_f32 v[164:165], v[134:135], s[28:29] op_sel_hi:[1,0]
	v_pk_mul_f32 v[168:169], v[142:143], s[28:29] op_sel_hi:[1,0]
	v_pk_mul_f32 v[2:3], v[132:133], s[28:29] op_sel_hi:[1,0]
	v_max_f32_e32 v0, v164, v165
	v_pk_mul_f32 v[166:167], v[140:141], s[28:29] op_sel_hi:[1,0]
	v_max_f32_e32 v170, v168, v169
	v_max3_f32 v0, v2, v3, v0
	v_max3_f32 v170, v166, v167, v170
	s_mov_b32 s10, 0xff800000
	v_pk_mul_f32 v[172:173], v[138:139], s[28:29] op_sel_hi:[1,0]
	v_max3_f32 v0, v0, s10, v170
	v_pk_mul_f32 v[170:171], v[136:137], s[28:29] op_sel_hi:[1,0]
	v_max_f32_e32 v174, v172, v173
	v_pk_mul_f32 v[176:177], v[146:147], s[28:29] op_sel_hi:[1,0]
	v_max3_f32 v190, v170, v171, v174
	v_pk_mul_f32 v[174:175], v[144:145], s[28:29] op_sel_hi:[1,0]
	v_max_f32_e32 v191, v176, v177
	v_max3_f32 v191, v174, v175, v191
	v_max3_f32 v0, v0, v190, v191
	s_mov_b64 s[10:11], 0

; __device__ void moba_item(const P& p, int bh, int qt, char* smem) {
;     ...
;       float ps = 0.f;
;       bf16x8 pf[2];
; #pragma unroll
;       for (int st = 0; st < 2; ++st) {
;         float pv[8];
; #pragma unroll
;         for (int kt = 0; kt < 2; ++kt)
; #pragma unroll
;           for (int r = 0; r < 4; ++r) {
;             const float e = __builtin_amdgcn_exp2f(sacc[st][kt][r] - muse);
;             pv[kt * 4 + r] = e;
;             ps += e;
;           }
;         u32x4 u;
;         u.x = pk_bf16(pv[0], pv[1]); u.y = pk_bf16(pv[2], pv[3]); u.z = pk_bf16(pv[4], pv[5]); u.w = pk_bf16(pv[6], pv[7]);
;         pf[st] = *(bf16x8*)&u;
;       }
;       lrun = lrun * alpha + ps;
;       if (resc) {
; #pragma unroll
;         for (int d = 0; d < 8; ++d) oacc[d] *= alpha;
;       }
; #pragma unroll
;       for (int d = 0; d < 8; ++d) {
;         const int row = d * 16 + li;
; #pragma unroll
;         for (int st = 0; st < 2; ++st) {
;           const bf16x8 vf = *(const bf16x8*)(sV + row * 128 + (((st * 4 + g) ^ (li & 7)) << 4));
;           oacc[d] = __builtin_amdgcn_mfma_f32_16x16x32_bf16(vf, pf[st], oacc[d], 0, 0, 0);
;         }
;       }
.LBB0_624:
	v_add_u32_e32 v236, v181, v182
	v_add_u32_e32 v237, v181, v183
	ds_read_b128 v[194:197], v236 offset:16384
	ds_read_b128 v[198:201], v237 offset:16384
	ds_read_b128 v[202:205], v236 offset:18432
	ds_read_b128 v[220:223], v237 offset:18432
	ds_read_b128 v[224:227], v236 offset:20480
	ds_read_b128 v[228:231], v237 offset:20480
	ds_read_b128 v[232:235], v236 offset:22528
	ds_read_b128 v[4:7], v237 offset:22528
	ds_read_b128 v[8:11], v236 offset:24576
	ds_read_b128 v[12:15], v237 offset:24576
	ds_read_b128 v[16:19], v236 offset:26624
	v_sub_f32_e32 v2, v2, v132
	v_exp_f32_e32 v2, v2
	v_sub_f32_e32 v3, v3, v132
	v_exp_f32_e32 v3, v3
	v_sub_f32_e32 v134, v164, v132
	v_exp_f32_e32 v134, v134
	v_sub_f32_e32 v135, v165, v132
	v_exp_f32_e32 v135, v135
	v_sub_f32_e32 v136, v166, v132
	v_add_f32_e32 v133, 0, v2
	v_exp_f32_e32 v136, v136
	v_sub_f32_e32 v137, v167, v132
	v_add_f32_e32 v133, v3, v133
	v_exp_f32_e32 v137, v137
	v_sub_f32_e32 v138, v168, v132
	v_add_f32_e32 v133, v134, v133
	v_exp_f32_e32 v138, v138
	v_add_f32_e32 v133, v135, v133
	v_sub_f32_e32 v139, v169, v132
	v_add_f32_e32 v133, v136, v133
	v_exp_f32_e32 v139, v139
	v_cvt_pk_bf16_f32 v140, v134, s0
	v_sub_f32_e32 v134, v170, v132
	v_add_f32_e32 v133, v137, v133
	v_cvt_pk_bf16_f32 v141, v135, s0
	v_exp_f32_e32 v134, v134
	v_sub_f32_e32 v135, v171, v132
	v_add_f32_e32 v133, v138, v133
	v_cvt_pk_bf16_f32 v142, v138, s0
	v_exp_f32_e32 v135, v135
	v_sub_f32_e32 v138, v172, v132
	v_exp_f32_e32 v138, v138
	v_sub_f32_e32 v143, v173, v132
	v_add_f32_e32 v133, v139, v133
	v_exp_f32_e32 v143, v143
	v_sub_f32_e32 v144, v174, v132
	v_add_f32_e32 v133, v134, v133
	v_exp_f32_e32 v144, v144
	v_sub_f32_e32 v145, v175, v132
	v_add_f32_e32 v133, v135, v133
	v_exp_f32_e32 v145, v145
	v_sub_f32_e32 v146, v176, v132
	v_add_f32_e32 v133, v138, v133
	v_exp_f32_e32 v146, v146
	v_sub_f32_e32 v132, v177, v132
	v_add_f32_e32 v133, v143, v133
	v_exp_f32_e32 v132, v132
	v_add_f32_e32 v133, v144, v133
	v_add_f32_e32 v133, v145, v133
	v_add_f32_e32 v133, v146, v133
	v_add_f32_e32 v147, v132, v133
	v_fmac_f32_e32 v147, v188, v0
	v_add_u32_e32 v0, v181, v182
	v_cvt_pk_bf16_f32 v164, v134, s0
	v_cvt_pk_bf16_f32 v165, v135, s0
	v_cvt_pk_bf16_f32 v168, v132, s0
	v_cvt_pk_bf16_f32 v2, v2, s0
	v_cvt_pk_bf16_f32 v3, v3, s0
	v_cvt_pk_bf16_f32 v136, v136, s0
	v_cvt_pk_bf16_f32 v137, v137, s0
	v_cvt_pk_bf16_f32 v139, v139, s0
	v_cvt_pk_bf16_f32 v166, v138, s0
	v_perm_b32 v138, v137, v136, s88
	v_perm_b32 v136, v3, v2, s88
	v_add_u32_e32 v2, v181, v183
	v_cvt_pk_bf16_f32 v167, v143, s0
	v_perm_b32 v137, v141, v140, s88
	v_perm_b32 v139, v139, v142, s88
	v_cvt_pk_bf16_f32 v144, v144, s0
	v_cvt_pk_bf16_f32 v145, v145, s0
	v_cvt_pk_bf16_f32 v146, v146, s0
	v_perm_b32 v134, v145, v144, s88
	v_perm_b32 v133, v167, v166, s88
	v_perm_b32 v132, v165, v164, s88
	v_perm_b32 v135, v168, v146, s88
	v_mov_b32_e32 v188, v147
	s_waitcnt lgkmcnt(0)
	v_mfma_f32_16x16x32_bf16 v[108:111], v[194:197], v[136:139], v[108:111]
	v_mfma_f32_16x16x32_bf16 v[112:115], v[202:205], v[136:139], v[112:115]
	v_mfma_f32_16x16x32_bf16 v[68:71], v[224:227], v[136:139], v[68:71]
	v_mfma_f32_16x16x32_bf16 v[76:79], v[232:235], v[136:139], v[76:79]
	v_mfma_f32_16x16x32_bf16 v[60:63], v[8:11], v[136:139], v[60:63]
	ds_read_b128 v[194:197], v237 offset:26624
	ds_read_b128 v[202:205], v236 offset:28672
	ds_read_b128 v[224:227], v237 offset:28672
	ds_read_b128 v[232:235], v236 offset:30720
	ds_read_b128 v[8:11], v237 offset:30720
	v_mfma_f32_16x16x32_bf16 v[108:111], v[198:201], v[132:135], v[108:111]
	v_mfma_f32_16x16x32_bf16 v[112:115], v[220:223], v[132:135], v[112:115]
	v_mfma_f32_16x16x32_bf16 v[68:71], v[228:231], v[132:135], v[68:71]
	v_mfma_f32_16x16x32_bf16 v[76:79], v[4:7], v[132:135], v[76:79]
	v_mfma_f32_16x16x32_bf16 v[60:63], v[12:15], v[132:135], v[60:63]
	v_mfma_f32_16x16x32_bf16 v[72:75], v[16:19], v[136:139], v[72:75]
	s_waitcnt lgkmcnt(0)
	v_mfma_f32_16x16x32_bf16 v[72:75], v[194:197], v[132:135], v[72:75]
	v_mfma_f32_16x16x32_bf16 v[52:55], v[202:205], v[136:139], v[52:55]
	v_mfma_f32_16x16x32_bf16 v[104:107], v[232:235], v[136:139], v[104:107]
	v_mfma_f32_16x16x32_bf16 v[52:55], v[224:227], v[132:135], v[52:55]
	v_mfma_f32_16x16x32_bf16 v[104:107], v[8:11], v[132:135], v[104:107]
	s_cmp_ge_i32 s27, s40
	s_cbranch_scc1 .LBB0_612
	s_branch .LBB0_626

; __device__ void moba_item(const P& p, int bh, int qt, char* smem) {
;     ...
;   auto step = [&](const int tt, u32x4 (&rk)[4], u32x4 (&rv)[4]) __attribute__((always_inline)) {
;     __syncthreads();
; #pragma unroll
;     for (int i = 0; i < 4; ++i) {
;       const int row = kr + 16 * i;
;       const int f = ((row >> 3) & 3) * 4 + (row & 3);
;       *(u32x4*)(sK + row * 256 + ((kc ^ f) << 4)) = rk[i];
;       const int vrow = vr + 32 * i;
;       *(u32x4*)(sV + vrow * 128 + ((vc ^ (vrow & 7)) << 4)) = rv[i];
;     }
;     __syncthreads();
;     if (tt + 2 < ntiles) {
;       const int k1 = (tt + 2) * 64;
; #pragma unroll
;       for (int i = 0; i < 4; ++i) {
;         rk[i] = *(const u32x4*)(Kp + (size_t)(k1 + kr + 16 * i) * 128 + kc * 8);
;         rv[i] = *(const u32x4*)(VT + (size_t)(vr + 32 * i) * 4096 + k1 + vc * 8);
;       }
;     }
;     const int blk = tt >> 2;
;     const bool own = (blk == qblk);
;     const bool rowvalid = own || ((mymask >> blk) & 1u);
;     if (__any(rowvalid)) {
;       const int key0 = tt * 64;
;       f32x4 sacc[2][2];
; #pragma unroll
;       for (int st = 0; st < 2; ++st)
; #pragma unroll
;         for (int kt = 0; kt < 2; ++kt) {
;           sacc[st][kt] = (f32x4){0.f, 0.f, 0.f, 0.f};
;           const int row = 32 * st + 8 * (li >> 2) + 4 * kt + (li & 3);
; #pragma unroll
;           for (int kk = 0; kk < 4; ++kk) {
;             const bf16x8 kf = *(const bf16x8*)(sK + row * 256 + (((kk * 4 + g) ^ li) << 4));
;             sacc[st][kt] = __builtin_amdgcn_mfma_f32_16x16x32_bf16(kf, qf[kk], sacc[st][kt], 0, 0, 0);
;           }
;         }
.LBB0_626:
	s_waitcnt vmcnt(0) lgkmcnt(0)
	s_barrier
	s_and_b64 vcc, exec, s[8:9]
	s_cbranch_vccnz .Lmoba_skipB
	s_add_i32 s32, s25, 128
	v_readfirstlane_b32 s98, v152
	v_readfirstlane_b32 s99, v153
	s_lshl_b32 s57, s32, 8
	s_add_u32 s98, s98, s57
	s_addc_u32 s99, s99, 0
	s_add_u32 m0, s79, 0x0
	s_nop 0
	global_load_lds_dwordx4 v252, s[98:99]
	s_add_u32 m0, s79, 0x1000
	s_add_u32 s98, s98, 0x1000
	s_addc_u32 s99, s99, 0
	global_load_lds_dwordx4 v253, s[98:99]
	s_add_u32 m0, s79, 0x2000
	s_add_u32 s98, s98, 0x1000
	s_addc_u32 s99, s99, 0
	global_load_lds_dwordx4 v252, s[98:99]
	s_add_u32 m0, s79, 0x3000
	s_add_u32 s98, s98, 0x1000
	s_addc_u32 s99, s99, 0
	global_load_lds_dwordx4 v253, s[98:99]
	v_readfirstlane_b32 s98, v156
	v_readfirstlane_b32 s99, v157
	s_lshl_b32 s57, s32, 1
	s_add_u32 s98, s98, s57
	s_addc_u32 s99, s99, 0
	s_add_u32 m0, s79, 0x4000
	s_nop 0
	global_load_lds_dwordx4 v254, s[98:99]
	s_add_u32 m0, s79, 0x5000
	s_add_u32 s98, s98, 0x40000
	s_addc_u32 s99, s99, 0
	global_load_lds_dwordx4 v254, s[98:99]
	s_add_u32 m0, s79, 0x6000
	s_add_u32 s98, s98, 0x40000
	s_addc_u32 s99, s99, 0
	global_load_lds_dwordx4 v254, s[98:99]
	s_add_u32 m0, s79, 0x7000
	s_add_u32 s98, s98, 0x40000
	s_addc_u32 s99, s99, 0
	global_load_lds_dwordx4 v254, s[98:99]
.Lmoba_skipB:
.LBB0_628:
	v_cndmask_b32_e64 v0, 0, 1, s[6:7]
	v_cmp_ne_u32_e32 vcc, 0, v0
	s_cbranch_vccz .LBB0_612
	v_add_u32_e32 v2, v155, v151
	v_add_u32_e32 v3, v155, v178
	v_add_u32_e32 v168, v155, v179
	v_add_u32_e32 v169, v155, v180
	s_cmp_eq_u32 s24, s27
	s_cselect_b64 s[0:1], -1, 0
	s_and_b64 vcc, exec, s[0:1]
	s_mov_b64 s[10:11], s[0:1]
	ds_read_b128 v[194:197], v2 offset:32768
	ds_read_b128 v[198:201], v2 offset:33792
	ds_read_b128 v[202:205], v2 offset:40960
	ds_read_b128 v[220:223], v2 offset:41984
	ds_read_b128 v[224:227], v3 offset:32768
	ds_read_b128 v[228:231], v3 offset:33792
	ds_read_b128 v[232:235], v3 offset:40960
	ds_read_b128 v[4:7], v3 offset:41984
	ds_read_b128 v[8:11], v168 offset:32768
	ds_read_b128 v[12:15], v168 offset:33792
	ds_read_b128 v[16:19], v168 offset:40960
	ds_read_b128 v[164:167], v168 offset:41984
	s_waitcnt lgkmcnt(8)
	v_mfma_f32_16x16x32_bf16 v[132:135], v[194:197], v[20:23], 0
	v_mfma_f32_16x16x32_bf16 v[140:143], v[198:201], v[20:23], 0
	v_mfma_f32_16x16x32_bf16 v[136:139], v[202:205], v[20:23], 0
	v_mfma_f32_16x16x32_bf16 v[144:147], v[220:223], v[20:23], 0
	ds_read_b128 v[194:197], v169 offset:32768
	ds_read_b128 v[198:201], v169 offset:33792
	ds_read_b128 v[202:205], v169 offset:40960
	ds_read_b128 v[220:223], v169 offset:41984
	s_waitcnt lgkmcnt(8)
	v_mfma_f32_16x16x32_bf16 v[132:135], v[224:227], v[24:27], v[132:135]
	v_mfma_f32_16x16x32_bf16 v[140:143], v[228:231], v[24:27], v[140:143]
	v_mfma_f32_16x16x32_bf16 v[136:139], v[232:235], v[24:27], v[136:139]
	v_mfma_f32_16x16x32_bf16 v[144:147], v[4:7], v[24:27], v[144:147]
	s_waitcnt lgkmcnt(4)
	v_mfma_f32_16x16x32_bf16 v[132:135], v[8:11], v[28:31], v[132:135]
	v_mfma_f32_16x16x32_bf16 v[140:143], v[12:15], v[28:31], v[140:143]
	v_mfma_f32_16x16x32_bf16 v[136:139], v[16:19], v[28:31], v[136:139]
	v_mfma_f32_16x16x32_bf16 v[144:147], v[164:167], v[28:31], v[144:147]
	s_waitcnt lgkmcnt(0)
	v_mfma_f32_16x16x32_bf16 v[132:135], v[194:197], v[32:35], v[132:135]
	v_mfma_f32_16x16x32_bf16 v[140:143], v[198:201], v[32:35], v[140:143]
	v_mfma_f32_16x16x32_bf16 v[136:139], v[202:205], v[32:35], v[136:139]
	v_mfma_f32_16x16x32_bf16 v[144:147], v[220:223], v[32:35], v[144:147]
	s_nop 7
	s_cbranch_vccnz .LBB0_632
	v_cmp_ne_u32_e32 vcc, 0, v0
	s_cmp_eq_u64 vcc, exec
	s_mov_b64 s[10:11], -1
	s_cbranch_scc0 .LBB0_632
	s_mov_b32 s28, 0x3e0293ee
	v_pk_mul_f32 v[164:165], v[134:135], s[28:29] op_sel_hi:[1,0]
	v_pk_mul_f32 v[2:3], v[132:133], s[28:29] op_sel_hi:[1,0]
	v_max_f32_e32 v166, v164, v165
	v_pk_mul_f32 v[168:169], v[142:143], s[28:29] op_sel_hi:[1,0]
	v_max3_f32 v170, v2, v3, v166
	v_pk_mul_f32 v[166:167], v[140:141], s[28:29] op_sel_hi:[1,0]
	v_max_f32_e32 v171, v168, v169
	v_max3_f32 v171, v166, v167, v171
	s_mov_b32 s10, 0xff800000
	v_pk_mul_f32 v[172:173], v[138:139], s[28:29] op_sel_hi:[1,0]
	v_max3_f32 v189, v170, s10, v171
	v_pk_mul_f32 v[170:171], v[136:137], s[28:29] op_sel_hi:[1,0]
	v_max_f32_e32 v174, v172, v173
	v_pk_mul_f32 v[176:177], v[146:147], s[28:29] op_sel_hi:[1,0]
	v_max3_f32 v191, v170, v171, v174
	v_pk_mul_f32 v[174:175], v[144:145], s[28:29] op_sel_hi:[1,0]
	v_max_f32_e32 v192, v176, v177
	v_max3_f32 v192, v174, v175, v192
	v_max3_f32 v189, v189, v191, v192
	s_mov_b64 s[10:11], 0

; __device__ void moba_item(const P& p, int bh, int qt, char* smem) {
;     ...
;       float ps = 0.f;
;       bf16x8 pf[2];
; #pragma unroll
;       for (int st = 0; st < 2; ++st) {
;         float pv[8];
; #pragma unroll
;         for (int kt = 0; kt < 2; ++kt)
; #pragma unroll
;           for (int r = 0; r < 4; ++r) {
;             const float e = __builtin_amdgcn_exp2f(sacc[st][kt][r] - muse);
;             pv[kt * 4 + r] = e;
;             ps += e;
;           }
;         u32x4 u;
;         u.x = pk_bf16(pv[0], pv[1]); u.y = pk_bf16(pv[2], pv[3]); u.z = pk_bf16(pv[4], pv[5]); u.w = pk_bf16(pv[6], pv[7]);
;         pf[st] = *(bf16x8*)&u;
;       }
;       lrun = lrun * alpha + ps;
;       if (resc) {
; #pragma unroll
;         for (int d = 0; d < 8; ++d) oacc[d] *= alpha;
;       }
; #pragma unroll
;       for (int d = 0; d < 8; ++d) {
;         const int row = d * 16 + li;
; #pragma unroll
;         for (int st = 0; st < 2; ++st) {
;           const bf16x8 vf = *(const bf16x8*)(sV + row * 128 + (((st * 4 + g) ^ (li & 7)) << 4));
;           oacc[d] = __builtin_amdgcn_mfma_f32_16x16x32_bf16(vf, pf[st], oacc[d], 0, 0, 0);
;         }
;       }
;     }
;     };
;   for (int tt = 0; tt < ntiles; tt += 2) {
;     step(tt, rkA, rvA);
;     if (tt + 1 < ntiles) step(tt + 1, rkB, rvB);
.LBB0_636:
	v_add_u32_e32 v236, v181, v182
	v_add_u32_e32 v237, v181, v183
	ds_read_b128 v[194:197], v236 offset:49152
	ds_read_b128 v[198:201], v237 offset:49152
	ds_read_b128 v[202:205], v236 offset:51200
	ds_read_b128 v[220:223], v237 offset:51200
	ds_read_b128 v[224:227], v236 offset:53248
	ds_read_b128 v[228:231], v237 offset:53248
	ds_read_b128 v[232:235], v236 offset:55296
	ds_read_b128 v[4:7], v237 offset:55296
	ds_read_b128 v[8:11], v236 offset:57344
	ds_read_b128 v[12:15], v237 offset:57344
	ds_read_b128 v[16:19], v236 offset:59392
	v_sub_f32_e32 v2, v2, v132
	v_exp_f32_e32 v2, v2
	v_sub_f32_e32 v3, v3, v132
	v_exp_f32_e32 v3, v3
	v_sub_f32_e32 v134, v164, v132
	v_exp_f32_e32 v134, v134
	v_sub_f32_e32 v135, v165, v132
	v_exp_f32_e32 v135, v135
	v_sub_f32_e32 v136, v166, v132
	v_add_f32_e32 v133, 0, v2
	v_exp_f32_e32 v136, v136
	v_sub_f32_e32 v137, v167, v132
	v_add_f32_e32 v133, v3, v133
	v_exp_f32_e32 v137, v137
	v_sub_f32_e32 v138, v168, v132
	v_add_f32_e32 v133, v134, v133
	v_exp_f32_e32 v138, v138
	v_add_f32_e32 v133, v135, v133
	v_sub_f32_e32 v139, v169, v132
	v_add_f32_e32 v133, v136, v133
	v_exp_f32_e32 v139, v139
	v_cvt_pk_bf16_f32 v140, v134, s0
	v_sub_f32_e32 v134, v170, v132
	v_add_f32_e32 v133, v137, v133
	v_cvt_pk_bf16_f32 v141, v135, s0
	v_exp_f32_e32 v134, v134
	v_sub_f32_e32 v135, v171, v132
	v_add_f32_e32 v133, v138, v133
	v_cvt_pk_bf16_f32 v142, v138, s0
	v_exp_f32_e32 v135, v135
	v_sub_f32_e32 v138, v172, v132
	v_exp_f32_e32 v138, v138
	v_sub_f32_e32 v143, v173, v132
	v_add_f32_e32 v133, v139, v133
	v_exp_f32_e32 v143, v143
	v_sub_f32_e32 v144, v174, v132
	v_add_f32_e32 v133, v134, v133
	v_exp_f32_e32 v144, v144
	v_sub_f32_e32 v145, v175, v132
	v_add_f32_e32 v133, v135, v133
	v_exp_f32_e32 v145, v145
	v_sub_f32_e32 v146, v176, v132
	v_add_f32_e32 v133, v138, v133
	v_exp_f32_e32 v146, v146
	v_sub_f32_e32 v132, v177, v132
	v_add_f32_e32 v133, v143, v133
	v_exp_f32_e32 v132, v132
	v_add_f32_e32 v133, v144, v133
	v_add_f32_e32 v133, v145, v133
	v_add_f32_e32 v133, v146, v133
	v_add_f32_e32 v147, v132, v133
	v_fmac_f32_e32 v147, v188, v0
	v_add_u32_e32 v0, v181, v182
	v_cvt_pk_bf16_f32 v164, v134, s0
	v_cvt_pk_bf16_f32 v165, v135, s0
	v_cvt_pk_bf16_f32 v168, v132, s0
	v_cvt_pk_bf16_f32 v2, v2, s0
	v_cvt_pk_bf16_f32 v3, v3, s0
	v_cvt_pk_bf16_f32 v136, v136, s0
	v_cvt_pk_bf16_f32 v137, v137, s0
	v_cvt_pk_bf16_f32 v139, v139, s0
	v_cvt_pk_bf16_f32 v166, v138, s0
	v_perm_b32 v138, v137, v136, s88
	v_perm_b32 v136, v3, v2, s88
	v_add_u32_e32 v2, v181, v183
	v_cvt_pk_bf16_f32 v167, v143, s0
	v_perm_b32 v137, v141, v140, s88
	v_perm_b32 v139, v139, v142, s88
	v_cvt_pk_bf16_f32 v144, v144, s0
	v_cvt_pk_bf16_f32 v145, v145, s0
	v_cvt_pk_bf16_f32 v146, v146, s0
	v_perm_b32 v134, v145, v144, s88
	v_perm_b32 v133, v167, v166, s88
	v_perm_b32 v132, v165, v164, s88
	v_perm_b32 v135, v168, v146, s88
	v_mov_b32_e32 v188, v147
	s_waitcnt lgkmcnt(0)
	v_mfma_f32_16x16x32_bf16 v[108:111], v[194:197], v[136:139], v[108:111]
	v_mfma_f32_16x16x32_bf16 v[112:115], v[202:205], v[136:139], v[112:115]
	v_mfma_f32_16x16x32_bf16 v[68:71], v[224:227], v[136:139], v[68:71]
	v_mfma_f32_16x16x32_bf16 v[76:79], v[232:235], v[136:139], v[76:79]
	v_mfma_f32_16x16x32_bf16 v[60:63], v[8:11], v[136:139], v[60:63]
	ds_read_b128 v[194:197], v237 offset:59392
	ds_read_b128 v[202:205], v236 offset:61440
	ds_read_b128 v[224:227], v237 offset:61440
	ds_read_b128 v[232:235], v236 offset:63488
	ds_read_b128 v[8:11], v237 offset:63488
	v_mfma_f32_16x16x32_bf16 v[108:111], v[198:201], v[132:135], v[108:111]
	v_mfma_f32_16x16x32_bf16 v[112:115], v[220:223], v[132:135], v[112:115]
	v_mfma_f32_16x16x32_bf16 v[68:71], v[228:231], v[132:135], v[68:71]
	v_mfma_f32_16x16x32_bf16 v[76:79], v[4:7], v[132:135], v[76:79]
	v_mfma_f32_16x16x32_bf16 v[60:63], v[12:15], v[132:135], v[60:63]
	v_mfma_f32_16x16x32_bf16 v[72:75], v[16:19], v[136:139], v[72:75]
	s_waitcnt lgkmcnt(0)
	v_mfma_f32_16x16x32_bf16 v[72:75], v[194:197], v[132:135], v[72:75]
	v_mfma_f32_16x16x32_bf16 v[52:55], v[202:205], v[136:139], v[52:55]
	v_mfma_f32_16x16x32_bf16 v[104:107], v[232:235], v[136:139], v[104:107]
	v_mfma_f32_16x16x32_bf16 v[52:55], v[224:227], v[132:135], v[52:55]
	v_mfma_f32_16x16x32_bf16 v[104:107], v[8:11], v[132:135], v[104:107]
	s_andn2_b64 vcc, exec, s[8:9]
	s_addk_i32 s25, 0x80
	s_cbranch_vccnz .LBB0_613
	s_branch .LBB0_454

; __global__ void __launch_bounds__(256, 2) fwd_kernel(P p) {
;   __shared__ __attribute__((aligned(16))) char smem[65536];
	.amdhsa_kernel _Z10fwd_kernel1P
		.amdhsa_group_segment_fixed_size 73744
		.amdhsa_private_segment_fixed_size 0
		.amdhsa_kernarg_size 376
		.amdhsa_user_sgpr_count 2
		.amdhsa_user_sgpr_dispatch_ptr 0
		.amdhsa_user_sgpr_queue_ptr 0
		.amdhsa_user_sgpr_kernarg_segment_ptr 1
		.amdhsa_user_sgpr_dispatch_id 0
		.amdhsa_user_sgpr_kernarg_preload_length 0
		.amdhsa_user_sgpr_kernarg_preload_offset 0
		.amdhsa_user_sgpr_private_segment_size 0
		.amdhsa_uses_dynamic_stack 0
		.amdhsa_enable_private_segment 0
		.amdhsa_system_sgpr_workgroup_id_x 1
		.amdhsa_system_sgpr_workgroup_id_y 0
		.amdhsa_system_sgpr_workgroup_id_z 0
		.amdhsa_system_sgpr_workgroup_info 0
		.amdhsa_system_vgpr_workitem_id 2
		.amdhsa_next_free_vgpr 256
		.amdhsa_next_free_sgpr 100
		.amdhsa_accum_offset 256
		.amdhsa_reserve_vcc 1
		.amdhsa_float_round_mode_32 0
		.amdhsa_float_round_mode_16_64 0
		.amdhsa_float_denorm_mode_32 3
		.amdhsa_float_denorm_mode_16_64 3
		.amdhsa_dx10_clamp 1
		.amdhsa_ieee_mode 1
		.amdhsa_fp16_overflow 0
		.amdhsa_tg_split 0
		.amdhsa_exception_fp_ieee_invalid_op 0
		.amdhsa_exception_fp_denorm_src 0
		.amdhsa_exception_fp_ieee_div_zero 0
		.amdhsa_exception_fp_ieee_overflow 0
		.amdhsa_exception_fp_ieee_underflow 0
		.amdhsa_exception_fp_ieee_inexact 0
		.amdhsa_exception_int_div_zero 0
	.end_amdhsa_kernel

; __global__ void __launch_bounds__(256, 2) fwd_kernel(P p) {
;   __shared__ __attribute__((aligned(16))) char smem[65536];
amdhsa.kernels:
  - .agpr_count:     0
    .args:
      - .offset:         0
        .size:           120
        .value_kind:     by_value
      - .offset:         120
        .size:           4
        .value_kind:     hidden_block_count_x
      - .offset:         124
        .size:           4
        .value_kind:     hidden_block_count_y
      - .offset:         128
        .size:           4
        .value_kind:     hidden_block_count_z
      - .offset:         132
        .size:           2
        .value_kind:     hidden_group_size_x
      - .offset:         134
        .size:           2
        .value_kind:     hidden_group_size_y
      - .offset:         136
        .size:           2
        .value_kind:     hidden_group_size_z
      - .offset:         138
        .size:           2
        .value_kind:     hidden_remainder_x
      - .offset:         140
        .size:           2
        .value_kind:     hidden_remainder_y
      - .offset:         142
        .size:           2
        .value_kind:     hidden_remainder_z
      - .offset:         160
        .size:           8
        .value_kind:     hidden_global_offset_x
      - .offset:         168
        .size:           8
        .value_kind:     hidden_global_offset_y
      - .offset:         176
        .size:           8
        .value_kind:     hidden_global_offset_z
      - .offset:         184
        .size:           2
        .value_kind:     hidden_grid_dims
      - .offset:         208
        .size:           8
        .value_kind:     hidden_multigrid_sync_arg
    .group_segment_fixed_size: 73744
    .kernarg_segment_align: 8
    .kernarg_segment_size: 376
    .language:       OpenCL C
    .language_version:
      - 2
      - 0
    .max_flat_workgroup_size: 256
    .name:           _Z10fwd_kernel1P
    .private_segment_fixed_size: 0
    .sgpr_count:     106
    .sgpr_spill_count: 66
    .symbol:         _Z10fwd_kernel1P.kd
    .uniform_work_group_size: 1
    .uses_dynamic_stack: false
    .vgpr_count:     256
    .vgpr_spill_count: 0
    .wavefront_size: 64
